# + e10: scan_item executes the end-of-chunk workgroup barrier only on the loop-exit path (the next iteration's first barrier provides the ordering)
# speedup vs baseline: 1.0034x; 1.0034x over previous
; #define LBAR() asm volatile("s_waitcnt lgkmcnt(0)\n\ts_barrier" ::: "memory")
; template <bool OUT>
; __device__ __forceinline__ void scan_item(LAS unsigned char* lds, unsigned char* ws, const float* hgn_l, int item, int tid_in, int wid, int lane_in) {
;     ...
;             LBAR();
;         }
.LBB0_389:
	s_waitcnt lgkmcnt(0)
	s_add_i32 s26, s26, -1
	s_add_i32 s38, s38, 1
	s_cmp_eq_u32 s26, -2
	s_cbranch_scc0 .Lscan_cont
	s_barrier
	s_branch .LBB0_361
.Lscan_cont:
	s_waitcnt lgkmcnt(0)
	v_mov_b32_e32 v32, v0
	v_mov_b32_e32 v33, v1
	v_mov_b32_e32 v34, v2
	v_mov_b32_e32 v35, v3
	v_mov_b32_e32 v36, v4
	v_mov_b32_e32 v37, v5
	v_mov_b32_e32 v38, v6
	v_mov_b32_e32 v39, v7
	v_mov_b32_e32 v40, v8
	v_mov_b32_e32 v41, v9
	v_mov_b32_e32 v42, v10
	v_mov_b32_e32 v43, v11
	v_mov_b32_e32 v44, v12
	v_mov_b32_e32 v45, v13
	v_mov_b32_e32 v46, v14
	v_mov_b32_e32 v47, v15
	v_mov_b32_e32 v48, v16
	v_mov_b32_e32 v49, v17
	v_mov_b32_e32 v50, v18
	v_mov_b32_e32 v51, v19
	v_mov_b32_e32 v52, v20
	v_mov_b32_e32 v53, v21
	v_mov_b32_e32 v54, v22
	v_mov_b32_e32 v55, v23
	v_mov_b32_e32 v56, v24
	v_mov_b32_e32 v57, v25
	v_mov_b32_e32 v58, v26
	v_mov_b32_e32 v59, v27
	v_mov_b32_e32 v60, v28
	v_mov_b32_e32 v61, v29
	v_mov_b32_e32 v62, v30
	v_mov_b32_e32 v63, v31
	s_branch .LBB0_365
